# LRU: next tile A-frag reads + gate MFMAs hoisted into previous tile gate math (software pipelining, no math change)
# speedup vs baseline: 1.0574x; 1.0083x over previous
; __device__ __forceinline__ float bf2f(bf16_t b) { return __uint_as_float(((unsigned)b) << 16); }
; __device__ __forceinline__ float sigmoidf(float z) { return __builtin_amdgcn_rcpf(1.0f + __expf(-z)); }
; __device__ void lru_fused_phase(const int bid, const int nblk, bf16_t* __restrict__ U, bf16_t* __restrict__ HF, const bf16_t* __restrict__ Wg, const float* __restrict__ cw, const float* __restrict__ cb, ...
;     ...
;                 for (int rti = 0; rti < 4; ++rti) {
;                     const int rt = e == 0 ? rti : 3 - rti;
;                     const long grow = rowb + 64 * k + 16 * rt + 4 * fq;
;                     unsigned short hfv[4], gtv[4];
;                     if (e == 1) {
; #pragma unroll
;                         for (int j = 0; j < 4; ++j) { hfv[j] = HF[(grow + j) * DRNN + ch]; gtv[j] = U[(grow + j) * (2 * DRNN) + ch]; }
;                     }
;                     f32x4 za = {0.f, 0.f, 0.f, 0.f}, zi = {0.f, 0.f, 0.f, 0.f};
; #pragma unroll
;                     for (int s = 0; s < 4; ++s) {
;                         const bf16x8 af = *(const bf16x8*)(buf + (16 * rt + fr) * RS + (32 * s + 8 * fq) * 2);
;                         za = __builtin_amdgcn_mfma_f32_16x16x32_bf16(af, Bf[0][s], za, 0, 0, 0);
;                         zi = __builtin_amdgcn_mfma_f32_16x16x32_bf16(af, Bf[1][s], zi, 0, 0, 0);
;                     }
;                     float av[4], bv[4];
; #pragma unroll
;                     for (int j = 0; j < 4; ++j) {
;                         const float c = bf2f(*(const unsigned short*)(buf + (16 * rt + 4 * fq + j) * RS + chl * 2));
;                         const float r = sigmoidf(za[j] + ba), ig = sigmoidf(zi[j] + bi_);
;                         const float la = -sp * r;
;                         av[j] = __expf(la);
;                         bv[j] = __builtin_sqrtf(fmaxf(1.0f - av[j] * av[j], 0.f)) * ig * c;
;                     }
.LBB0_119:
	s_bitcmp1_b32 s2, 0
	s_cselect_b32 s2, 0x4400, 0
	s_add_i32 s2, s2, 0
	v_add_u32_e32 v104, s2, v8
	v_add_u32_e32 v106, v104, v98
	ds_read_b128 v[36:39], v106
	ds_read_b128 v[108:111], v106 offset:64
	v_add_u32_e32 v10, s2, v74
	s_mov_b64 s[2:3], -1
	s_waitcnt lgkmcnt(1)
	v_mfma_f32_16x16x32_bf16 v[40:43], v[36:39], v[0:3], 0
	v_mfma_f32_16x16x32_bf16 v[36:39], v[36:39], v[20:23], 0
	s_waitcnt lgkmcnt(0)
	v_mfma_f32_16x16x32_bf16 v[40:43], v[108:111], v[4:7], v[40:43]
	v_mfma_f32_16x16x32_bf16 v[36:39], v[108:111], v[24:27], v[36:39]
	ds_read_b128 v[108:111], v106 offset:128
	s_waitcnt lgkmcnt(0)
	v_mfma_f32_16x16x32_bf16 v[40:43], v[108:111], v[12:15], v[40:43]
	v_mfma_f32_16x16x32_bf16 v[36:39], v[108:111], v[28:31], v[36:39]
	ds_read_b128 v[108:111], v106 offset:192
	v_add_u32_e32 v106, v10, v99
	s_waitcnt lgkmcnt(0)
	v_mfma_f32_16x16x32_bf16 v[40:43], v[108:111], v[16:19], v[40:43]
	s_nop 7
	v_add_f32_e32 v40, v82, v40
	v_mfma_f32_16x16x32_bf16 v[36:39], v[108:111], v[32:35], v[36:39]
	v_or_b32_e32 v152, s70, v47
	v_xor_b32_e32 v152, 16, v152
	v_mad_u32_u24 v152, v152, s35, v104
	ds_read_b128 v[128:131], v152
	ds_read_b128 v[132:135], v152 offset:64
	ds_read_b128 v[136:139], v152 offset:128
	ds_read_b128 v[140:143], v152 offset:192
	v_mul_f32_e32 v40, 0xbfb8aa3b, v40
	v_exp_f32_e32 v40, v40
	v_add_f32_e32 v41, v82, v41
	v_mul_f32_e32 v41, 0xbfb8aa3b, v41
	v_exp_f32_e32 v41, v41
	s_nop 2
	v_add_f32_e32 v36, v83, v36
	v_mul_f32_e32 v36, 0xbfb8aa3b, v36
	v_add_f32_e32 v40, 1.0, v40
	v_exp_f32_e32 v36, v36
	v_rcp_f32_e32 v40, v40
	v_add_f32_e32 v37, v83, v37
	v_mul_f32_e32 v37, 0xbfb8aa3b, v37
	v_add_f32_e32 v36, 1.0, v36
	v_rcp_f32_e32 v109, v36
	v_mul_f32_e32 v36, v40, v86
	v_mul_f32_e32 v36, 0xbfb8aa3b, v36
	v_exp_f32_e32 v36, v36
	v_add_f32_e32 v41, 1.0, v41
	v_exp_f32_e32 v37, v37
	v_rcp_f32_e32 v41, v41
	v_fma_f32 v40, -v36, v36, 1.0
	v_max_f32_e32 v40, 0, v40
	v_add_f32_e32 v37, 1.0, v37
	v_sqrt_f32_e32 v40, v40
	s_nop 0
	v_add_f32_e32 v42, v82, v42
	v_mul_f32_e32 v42, 0xbfb8aa3b, v42
	v_exp_f32_e32 v42, v42
	v_add_f32_e32 v38, v83, v38
	v_mul_f32_e32 v38, 0xbfb8aa3b, v38
	v_add_f32_e32 v42, 1.0, v42
	v_exp_f32_e32 v38, v38
	v_rcp_f32_e32 v42, v42
	v_mul_f32_e32 v40, v109, v40
	v_rcp_f32_e32 v109, v37
	v_mul_f32_e32 v37, v41, v86
	v_mul_f32_e32 v37, 0xbfb8aa3b, v37
	v_exp_f32_e32 v37, v37
	v_add_f32_e32 v38, 1.0, v38
	ds_read_u16 v108, v106
	v_add_f32_e32 v43, v82, v43
	v_fma_f32 v41, -v37, v37, 1.0
	v_max_f32_e32 v41, 0, v41
	s_waitcnt lgkmcnt(0)
	v_lshlrev_b32_e32 v108, 16, v108
	v_sqrt_f32_e32 v41, v41
	s_nop 0
	v_mul_f32_e32 v40, v40, v108
	ds_read_u16 v108, v106 offset:272
	v_mul_f32_e32 v43, 0xbfb8aa3b, v43
	v_exp_f32_e32 v43, v43
	s_waitcnt lgkmcnt(0)
	v_lshlrev_b32_e32 v108, 16, v108
	v_add_f32_e32 v39, v83, v39
	s_waitcnt lgkmcnt(0)
	v_mfma_f32_16x16x32_bf16 v[144:147], v[128:131], v[0:3], 0
	v_mfma_f32_16x16x32_bf16 v[148:151], v[128:131], v[20:23], 0
	v_mfma_f32_16x16x32_bf16 v[144:147], v[132:135], v[4:7], v[144:147]
	v_mfma_f32_16x16x32_bf16 v[148:151], v[132:135], v[24:27], v[148:151]
	v_mfma_f32_16x16x32_bf16 v[144:147], v[136:139], v[12:15], v[144:147]
	v_mfma_f32_16x16x32_bf16 v[148:151], v[136:139], v[28:31], v[148:151]
	v_mfma_f32_16x16x32_bf16 v[144:147], v[140:143], v[16:19], v[144:147]
	v_mfma_f32_16x16x32_bf16 v[148:151], v[140:143], v[32:35], v[148:151]
	v_mul_f32_e32 v39, 0xbfb8aa3b, v39
	v_add_f32_e32 v43, 1.0, v43
	v_mul_f32_e32 v41, v109, v41
	v_rcp_f32_e32 v109, v38
	v_mul_f32_e32 v38, v42, v86
	v_mul_f32_e32 v38, 0xbfb8aa3b, v38
	v_exp_f32_e32 v38, v38
	v_mul_f32_e32 v41, v41, v108
	ds_read_u16 v108, v106 offset:544
	v_exp_f32_e32 v39, v39
	v_fma_f32 v42, -v38, v38, 1.0
	v_max_f32_e32 v42, 0, v42
	v_rcp_f32_e32 v43, v43
	v_sqrt_f32_e32 v42, v42
	s_nop 0
	s_waitcnt lgkmcnt(0)
	v_lshlrev_b32_e32 v108, 16, v108
	v_add_f32_e32 v39, 1.0, v39
	ds_read_u16 v106, v106 offset:816
	s_waitcnt lgkmcnt(0)
	v_lshlrev_b32_e32 v106, 16, v106
	s_nop 1
	s_nop 1
	v_mul_f32_e32 v42, v109, v42
	v_mul_f32_e32 v42, v42, v108
	v_rcp_f32_e32 v108, v39
	v_mul_f32_e32 v39, v43, v86
	v_mul_f32_e32 v39, 0xbfb8aa3b, v39
	v_exp_f32_e32 v39, v39
	s_nop 0
	v_fma_f32 v43, -v39, v39, 1.0
	v_max_f32_e32 v43, 0, v43
	s_nop 0
	v_sqrt_f32_e32 v43, v43
	s_nop 0
	s_nop 0
	s_nop 0
	s_nop 1
	s_nop 1
	v_mul_f32_e32 v43, v108, v43
	v_mul_f32_e32 v43, v43, v106
	s_and_b64 vcc, exec, s[64:65]
	s_cbranch_vccz .LBB0_121
	v_fma_f32 v108, v38, v43, v42
	v_mul_f32_e32 v109, v38, v39
	v_fma_f32 v111, v37, v108, v41
	v_mul_f32_e32 v110, v37, v109
	v_fma_f32 v112, v36, v111, v40
	v_mul_f32_e32 v106, v36, v110
	s_mov_b64 s[2:3], 0

; __device__ __forceinline__ float bf2f(bf16_t b) { return __uint_as_float(((unsigned)b) << 16); }
; __device__ __forceinline__ float sigmoidf(float z) { return __builtin_amdgcn_rcpf(1.0f + __expf(-z)); }
; __device__ void lru_fused_phase(const int bid, const int nblk, bf16_t* __restrict__ U, bf16_t* __restrict__ HF, const bf16_t* __restrict__ Wg, const float* __restrict__ cw, const float* __restrict__ cb, ...
;     ...
;                 for (int rti = 0; rti < 4; ++rti) {
;                     const int rt = e == 0 ? rti : 3 - rti;
;                     const long grow = rowb + 64 * k + 16 * rt + 4 * fq;
;                     unsigned short hfv[4], gtv[4];
;                     if (e == 1) {
; #pragma unroll
;                         for (int j = 0; j < 4; ++j) { hfv[j] = HF[(grow + j) * DRNN + ch]; gtv[j] = U[(grow + j) * (2 * DRNN) + ch]; }
;                     }
;                     f32x4 za = {0.f, 0.f, 0.f, 0.f}, zi = {0.f, 0.f, 0.f, 0.f};
; #pragma unroll
;                     for (int s = 0; s < 4; ++s) {
;                         const bf16x8 af = *(const bf16x8*)(buf + (16 * rt + fr) * RS + (32 * s + 8 * fq) * 2);
;                         za = __builtin_amdgcn_mfma_f32_16x16x32_bf16(af, Bf[0][s], za, 0, 0, 0);
;                         zi = __builtin_amdgcn_mfma_f32_16x16x32_bf16(af, Bf[1][s], zi, 0, 0, 0);
;                     }
;                     float av[4], bv[4];
; #pragma unroll
;                     for (int j = 0; j < 4; ++j) {
;                         const float c = bf2f(*(const unsigned short*)(buf + (16 * rt + 4 * fq + j) * RS + chl * 2));
;                         const float r = sigmoidf(za[j] + ba), ig = sigmoidf(zi[j] + bi_);
;                         const float la = -sp * r;
;                         av[j] = __expf(la);
;                         bv[j] = __builtin_sqrtf(fmaxf(1.0f - av[j] * av[j], 0.f)) * ig * c;
;                     }
.LBB0_142:
	s_mov_b64 s[2:3], -1
	s_waitcnt lgkmcnt(1)
	s_waitcnt lgkmcnt(0)
	s_waitcnt lgkmcnt(0)
	v_or_b32_e32 v105, s38, v46
	v_mad_u32_u24 v105, v105, s35, v10
	s_waitcnt lgkmcnt(0)
	v_or_b32_e32 v152, s70, v47
	v_xor_b32_e32 v152, 32, v152
	v_mad_u32_u24 v152, v152, s35, v104
	ds_read_b128 v[128:131], v152
	ds_read_b128 v[132:135], v152 offset:64
	ds_read_b128 v[136:139], v152 offset:128
	ds_read_b128 v[140:143], v152 offset:192
	v_add_f32_e32 v40, v82, v144
	v_mul_f32_e32 v40, 0xbfb8aa3b, v40
	v_exp_f32_e32 v40, v40
	v_add_f32_e32 v41, v82, v145
	v_mul_f32_e32 v41, 0xbfb8aa3b, v41
	v_exp_f32_e32 v41, v41
	s_nop 2
	v_add_f32_e32 v36, v83, v148
	v_mul_f32_e32 v36, 0xbfb8aa3b, v36
	v_add_f32_e32 v40, 1.0, v40
	v_exp_f32_e32 v36, v36
	v_rcp_f32_e32 v40, v40
	v_add_f32_e32 v37, v83, v149
	v_mul_f32_e32 v37, 0xbfb8aa3b, v37
	v_add_f32_e32 v36, 1.0, v36
	v_rcp_f32_e32 v109, v36
	v_mul_f32_e32 v36, v40, v86
	v_mul_f32_e32 v36, 0xbfb8aa3b, v36
	v_exp_f32_e32 v36, v36
	v_add_f32_e32 v41, 1.0, v41
	v_exp_f32_e32 v37, v37
	v_rcp_f32_e32 v41, v41
	v_fma_f32 v40, -v36, v36, 1.0
	v_max_f32_e32 v40, 0, v40
	v_add_f32_e32 v37, 1.0, v37
	v_sqrt_f32_e32 v40, v40
	s_nop 0
	v_add_f32_e32 v42, v82, v146
	v_mul_f32_e32 v42, 0xbfb8aa3b, v42
	v_exp_f32_e32 v42, v42
	v_add_f32_e32 v38, v83, v150
	v_mul_f32_e32 v38, 0xbfb8aa3b, v38
	v_add_f32_e32 v42, 1.0, v42
	v_exp_f32_e32 v38, v38
	v_rcp_f32_e32 v42, v42
	v_mul_f32_e32 v40, v109, v40
	v_rcp_f32_e32 v109, v37
	v_mul_f32_e32 v37, v41, v86
	v_mul_f32_e32 v37, 0xbfb8aa3b, v37
	v_exp_f32_e32 v37, v37
	v_add_f32_e32 v38, 1.0, v38
	ds_read_u16 v108, v105
	v_add_f32_e32 v43, v82, v147
	v_fma_f32 v41, -v37, v37, 1.0
	v_max_f32_e32 v41, 0, v41
	s_waitcnt lgkmcnt(0)
	v_lshlrev_b32_e32 v108, 16, v108
	v_sqrt_f32_e32 v41, v41
	s_nop 0
	v_mul_f32_e32 v40, v40, v108
	ds_read_u16 v108, v105 offset:272
	v_mul_f32_e32 v43, 0xbfb8aa3b, v43
	v_exp_f32_e32 v43, v43
	s_waitcnt lgkmcnt(0)
	v_lshlrev_b32_e32 v108, 16, v108
	v_add_f32_e32 v39, v83, v151
	s_waitcnt lgkmcnt(0)
	v_mfma_f32_16x16x32_bf16 v[144:147], v[128:131], v[0:3], 0
	v_mfma_f32_16x16x32_bf16 v[148:151], v[128:131], v[20:23], 0
	v_mfma_f32_16x16x32_bf16 v[144:147], v[132:135], v[4:7], v[144:147]
	v_mfma_f32_16x16x32_bf16 v[148:151], v[132:135], v[24:27], v[148:151]
	v_mfma_f32_16x16x32_bf16 v[144:147], v[136:139], v[12:15], v[144:147]
	v_mfma_f32_16x16x32_bf16 v[148:151], v[136:139], v[28:31], v[148:151]
	v_mfma_f32_16x16x32_bf16 v[144:147], v[140:143], v[16:19], v[144:147]
	v_mfma_f32_16x16x32_bf16 v[148:151], v[140:143], v[32:35], v[148:151]
	v_mul_f32_e32 v39, 0xbfb8aa3b, v39
	v_add_f32_e32 v43, 1.0, v43
	v_mul_f32_e32 v41, v109, v41
	v_rcp_f32_e32 v109, v38
	v_mul_f32_e32 v38, v42, v86
	v_mul_f32_e32 v38, 0xbfb8aa3b, v38
	v_exp_f32_e32 v38, v38
	v_mul_f32_e32 v41, v41, v108
	ds_read_u16 v108, v105 offset:544
	v_exp_f32_e32 v39, v39
	v_fma_f32 v42, -v38, v38, 1.0
	v_max_f32_e32 v42, 0, v42
	v_rcp_f32_e32 v43, v43
	v_sqrt_f32_e32 v42, v42
	s_nop 0
	s_waitcnt lgkmcnt(0)
	v_lshlrev_b32_e32 v108, 16, v108
	v_add_f32_e32 v39, 1.0, v39
	ds_read_u16 v105, v105 offset:816
	s_waitcnt lgkmcnt(0)
	v_lshlrev_b32_e32 v105, 16, v105
	s_nop 1
	s_nop 1
	v_mul_f32_e32 v42, v109, v42
	v_mul_f32_e32 v42, v42, v108
	v_rcp_f32_e32 v108, v39
	v_mul_f32_e32 v39, v43, v86
	v_mul_f32_e32 v39, 0xbfb8aa3b, v39
	v_exp_f32_e32 v39, v39
	s_nop 0
	v_fma_f32 v43, -v39, v39, 1.0
	v_max_f32_e32 v43, 0, v43
	s_nop 0
	v_sqrt_f32_e32 v43, v43
	s_nop 0
	s_nop 0
	s_nop 0
	s_nop 1
	s_nop 1
	v_mul_f32_e32 v43, v108, v43
	v_mul_f32_e32 v43, v43, v105
	s_and_b64 vcc, exec, s[8:9]
	s_cbranch_vccnz .LBB0_144
	v_fma_f32 v108, v38, v43, v42
	v_mul_f32_e32 v109, v38, v39
	v_fma_f32 v111, v37, v108, v41
	v_mul_f32_e32 v110, v37, v109
	v_fma_f32 v112, v36, v111, v40
	v_mul_f32_e32 v105, v36, v110
	s_mov_b64 s[2:3], 0

; __device__ __forceinline__ float bf2f(bf16_t b) { return __uint_as_float(((unsigned)b) << 16); }
; __device__ __forceinline__ float sigmoidf(float z) { return __builtin_amdgcn_rcpf(1.0f + __expf(-z)); }
; __device__ void lru_fused_phase(const int bid, const int nblk, bf16_t* __restrict__ U, bf16_t* __restrict__ HF, const bf16_t* __restrict__ Wg, const float* __restrict__ cw, const float* __restrict__ cb, ...
;     ...
;                 for (int rti = 0; rti < 4; ++rti) {
;                     const int rt = e == 0 ? rti : 3 - rti;
;                     const long grow = rowb + 64 * k + 16 * rt + 4 * fq;
;                     unsigned short hfv[4], gtv[4];
;                     if (e == 1) {
; #pragma unroll
;                         for (int j = 0; j < 4; ++j) { hfv[j] = HF[(grow + j) * DRNN + ch]; gtv[j] = U[(grow + j) * (2 * DRNN) + ch]; }
;                     }
;                     f32x4 za = {0.f, 0.f, 0.f, 0.f}, zi = {0.f, 0.f, 0.f, 0.f};
; #pragma unroll
;                     for (int s = 0; s < 4; ++s) {
;                         const bf16x8 af = *(const bf16x8*)(buf + (16 * rt + fr) * RS + (32 * s + 8 * fq) * 2);
;                         za = __builtin_amdgcn_mfma_f32_16x16x32_bf16(af, Bf[0][s], za, 0, 0, 0);
;                         zi = __builtin_amdgcn_mfma_f32_16x16x32_bf16(af, Bf[1][s], zi, 0, 0, 0);
;                     }
;                     float av[4], bv[4];
; #pragma unroll
;                     for (int j = 0; j < 4; ++j) {
;                         const float c = bf2f(*(const unsigned short*)(buf + (16 * rt + 4 * fq + j) * RS + chl * 2));
;                         const float r = sigmoidf(za[j] + ba), ig = sigmoidf(zi[j] + bi_);
;                         const float la = -sp * r;
;                         av[j] = __expf(la);
;                         bv[j] = __builtin_sqrtf(fmaxf(1.0f - av[j] * av[j], 0.f)) * ig * c;
;                     }
.LBB0_165:
	s_mov_b64 s[2:3], -1
	s_waitcnt lgkmcnt(1)
	s_waitcnt lgkmcnt(0)
	s_waitcnt lgkmcnt(0)
	v_or_b32_e32 v106, s38, v46
	v_mad_u32_u24 v106, v106, s35, v10
	s_waitcnt lgkmcnt(0)
	v_or_b32_e32 v152, s70, v47
	v_xor_b32_e32 v152, 48, v152
	v_mad_u32_u24 v152, v152, s35, v104
	ds_read_b128 v[128:131], v152
	ds_read_b128 v[132:135], v152 offset:64
	ds_read_b128 v[136:139], v152 offset:128
	ds_read_b128 v[140:143], v152 offset:192
	v_add_f32_e32 v40, v82, v144
	v_mul_f32_e32 v40, 0xbfb8aa3b, v40
	v_exp_f32_e32 v40, v40
	v_add_f32_e32 v41, v82, v145
	v_mul_f32_e32 v41, 0xbfb8aa3b, v41
	v_exp_f32_e32 v41, v41
	s_nop 2
	v_add_f32_e32 v36, v83, v148
	v_mul_f32_e32 v36, 0xbfb8aa3b, v36
	v_add_f32_e32 v40, 1.0, v40
	v_exp_f32_e32 v36, v36
	v_rcp_f32_e32 v40, v40
	v_add_f32_e32 v37, v83, v149
	v_mul_f32_e32 v37, 0xbfb8aa3b, v37
	v_add_f32_e32 v36, 1.0, v36
	v_rcp_f32_e32 v109, v36
	v_mul_f32_e32 v36, v40, v86
	v_mul_f32_e32 v36, 0xbfb8aa3b, v36
	v_exp_f32_e32 v36, v36
	v_add_f32_e32 v41, 1.0, v41
	v_exp_f32_e32 v37, v37
	v_rcp_f32_e32 v41, v41
	v_fma_f32 v40, -v36, v36, 1.0
	v_max_f32_e32 v40, 0, v40
	v_add_f32_e32 v37, 1.0, v37
	v_sqrt_f32_e32 v40, v40
	s_nop 0
	v_add_f32_e32 v42, v82, v146
	v_mul_f32_e32 v42, 0xbfb8aa3b, v42
	v_exp_f32_e32 v42, v42
	v_add_f32_e32 v38, v83, v150
	v_mul_f32_e32 v38, 0xbfb8aa3b, v38
	v_add_f32_e32 v42, 1.0, v42
	v_exp_f32_e32 v38, v38
	v_rcp_f32_e32 v42, v42
	v_mul_f32_e32 v40, v109, v40
	v_rcp_f32_e32 v109, v37
	v_mul_f32_e32 v37, v41, v86
	v_mul_f32_e32 v37, 0xbfb8aa3b, v37
	v_exp_f32_e32 v37, v37
	v_add_f32_e32 v38, 1.0, v38
	ds_read_u16 v108, v106
	v_add_f32_e32 v43, v82, v147
	v_fma_f32 v41, -v37, v37, 1.0
	v_max_f32_e32 v41, 0, v41
	s_waitcnt lgkmcnt(0)
	v_lshlrev_b32_e32 v108, 16, v108
	v_sqrt_f32_e32 v41, v41
	s_nop 0
	v_mul_f32_e32 v40, v40, v108
	ds_read_u16 v108, v106 offset:272
	v_mul_f32_e32 v43, 0xbfb8aa3b, v43
	v_exp_f32_e32 v43, v43
	s_waitcnt lgkmcnt(0)
	v_lshlrev_b32_e32 v108, 16, v108
	v_add_f32_e32 v39, v83, v151
	s_waitcnt lgkmcnt(0)
	v_mfma_f32_16x16x32_bf16 v[144:147], v[128:131], v[0:3], 0
	v_mfma_f32_16x16x32_bf16 v[148:151], v[128:131], v[20:23], 0
	v_mfma_f32_16x16x32_bf16 v[144:147], v[132:135], v[4:7], v[144:147]
	v_mfma_f32_16x16x32_bf16 v[148:151], v[132:135], v[24:27], v[148:151]
	v_mfma_f32_16x16x32_bf16 v[144:147], v[136:139], v[12:15], v[144:147]
	v_mfma_f32_16x16x32_bf16 v[148:151], v[136:139], v[28:31], v[148:151]
	v_mfma_f32_16x16x32_bf16 v[144:147], v[140:143], v[16:19], v[144:147]
	v_mfma_f32_16x16x32_bf16 v[148:151], v[140:143], v[32:35], v[148:151]
	v_mul_f32_e32 v39, 0xbfb8aa3b, v39
	v_add_f32_e32 v43, 1.0, v43
	v_mul_f32_e32 v41, v109, v41
	v_rcp_f32_e32 v109, v38
	v_mul_f32_e32 v38, v42, v86
	v_mul_f32_e32 v38, 0xbfb8aa3b, v38
	v_exp_f32_e32 v38, v38
	v_mul_f32_e32 v41, v41, v108
	ds_read_u16 v108, v106 offset:544
	v_exp_f32_e32 v39, v39
	v_fma_f32 v42, -v38, v38, 1.0
	v_max_f32_e32 v42, 0, v42
	v_rcp_f32_e32 v43, v43
	v_sqrt_f32_e32 v42, v42
	s_nop 0
	s_waitcnt lgkmcnt(0)
	v_lshlrev_b32_e32 v108, 16, v108
	v_add_f32_e32 v39, 1.0, v39
	ds_read_u16 v106, v106 offset:816
	s_waitcnt lgkmcnt(0)
	v_lshlrev_b32_e32 v106, 16, v106
	s_nop 1
	s_nop 1
	v_mul_f32_e32 v42, v109, v42
	v_mul_f32_e32 v42, v42, v108
	v_rcp_f32_e32 v108, v39
	v_mul_f32_e32 v39, v43, v86
	v_mul_f32_e32 v39, 0xbfb8aa3b, v39
	v_exp_f32_e32 v39, v39
	s_nop 0
	v_fma_f32 v43, -v39, v39, 1.0
	v_max_f32_e32 v43, 0, v43
	s_nop 0
	v_sqrt_f32_e32 v43, v43
	s_nop 0
	s_nop 0
	s_nop 0
	s_nop 1
	s_nop 1
	v_mul_f32_e32 v43, v108, v43
	v_mul_f32_e32 v43, v43, v106
	s_and_b64 vcc, exec, s[8:9]
	s_cbranch_vccnz .LBB0_167
	v_fma_f32 v108, v38, v43, v42
	v_mul_f32_e32 v109, v38, v39
	v_fma_f32 v111, v37, v108, v41
	v_mul_f32_e32 v110, v37, v109
	v_fma_f32 v112, v36, v111, v40
	v_mul_f32_e32 v106, v36, v110
	s_mov_b64 s[2:3], 0

; __device__ __forceinline__ float bf2f(bf16_t b) { return __uint_as_float(((unsigned)b) << 16); }
; __device__ __forceinline__ float sigmoidf(float z) { return __builtin_amdgcn_rcpf(1.0f + __expf(-z)); }
; __device__ void lru_fused_phase(const int bid, const int nblk, bf16_t* __restrict__ U, bf16_t* __restrict__ HF, const bf16_t* __restrict__ Wg, const float* __restrict__ cw, const float* __restrict__ cb, ...
;     ...
;                 for (int rti = 0; rti < 4; ++rti) {
;                     const int rt = e == 0 ? rti : 3 - rti;
;                     const long grow = rowb + 64 * k + 16 * rt + 4 * fq;
;                     unsigned short hfv[4], gtv[4];
;                     if (e == 1) {
; #pragma unroll
;                         for (int j = 0; j < 4; ++j) { hfv[j] = HF[(grow + j) * DRNN + ch]; gtv[j] = U[(grow + j) * (2 * DRNN) + ch]; }
;                     }
;                     f32x4 za = {0.f, 0.f, 0.f, 0.f}, zi = {0.f, 0.f, 0.f, 0.f};
; #pragma unroll
;                     for (int s = 0; s < 4; ++s) {
;                         const bf16x8 af = *(const bf16x8*)(buf + (16 * rt + fr) * RS + (32 * s + 8 * fq) * 2);
;                         za = __builtin_amdgcn_mfma_f32_16x16x32_bf16(af, Bf[0][s], za, 0, 0, 0);
;                         zi = __builtin_amdgcn_mfma_f32_16x16x32_bf16(af, Bf[1][s], zi, 0, 0, 0);
;                     }
;                     float av[4], bv[4];
; #pragma unroll
;                     for (int j = 0; j < 4; ++j) {
;                         const float c = bf2f(*(const unsigned short*)(buf + (16 * rt + 4 * fq + j) * RS + chl * 2));
;                         const float r = sigmoidf(za[j] + ba), ig = sigmoidf(zi[j] + bi_);
;                         const float la = -sp * r;
;                         av[j] = __expf(la);
;                         bv[j] = __builtin_sqrtf(fmaxf(1.0f - av[j] * av[j], 0.f)) * ig * c;
;                     }
.LBB0_188:
	s_mov_b64 s[2:3], -1
	s_waitcnt lgkmcnt(1)
	s_waitcnt lgkmcnt(0)
	s_waitcnt lgkmcnt(0)
	v_or_b32_e32 v104, s38, v46
	v_mad_u32_u24 v104, v104, s35, v10
	ds_read_u16 v10, v104
	s_waitcnt lgkmcnt(1)
	s_waitcnt lgkmcnt(0)
	v_lshlrev_b32_e32 v105, 16, v10
	s_nop 5
	v_add_f32_e32 v10, v82, v144
	v_mul_f32_e32 v10, 0xbfb8aa3b, v10
	v_exp_f32_e32 v10, v10
	v_add_f32_e32 v41, v82, v145
	v_mul_f32_e32 v41, 0xbfb8aa3b, v41
	v_add_f32_e32 v10, 1.0, v10
	v_rcp_f32_e32 v10, v10
	v_exp_f32_e32 v41, v41
	s_nop 2
	v_add_f32_e32 v36, v83, v148
	v_mul_f32_e32 v36, 0xbfb8aa3b, v36
	v_mul_f32_e32 v10, v10, v86
	v_mul_f32_e32 v10, 0xbfb8aa3b, v10
	v_exp_f32_e32 v10, v10
	v_exp_f32_e32 v36, v36
	v_add_f32_e32 v37, v83, v149
	v_mul_f32_e32 v37, 0xbfb8aa3b, v37
	v_fma_f32 v40, -v10, v10, 1.0
	v_max_f32_e32 v40, 0, v40
	v_add_f32_e32 v36, 1.0, v36
	v_sqrt_f32_e32 v40, v40
	s_nop 0
	v_rcp_f32_e32 v36, v36
	v_add_f32_e32 v41, 1.0, v41
	v_exp_f32_e32 v37, v37
	v_rcp_f32_e32 v41, v41
	v_add_f32_e32 v37, 1.0, v37
	v_add_f32_e32 v42, v82, v146
	v_mul_f32_e32 v42, 0xbfb8aa3b, v42
	v_exp_f32_e32 v42, v42
	v_mul_f32_e32 v36, v36, v40
	v_mul_f32_e32 v36, v36, v105
	v_rcp_f32_e32 v105, v37
	v_mul_f32_e32 v37, v41, v86
	v_mul_f32_e32 v37, 0xbfb8aa3b, v37
	v_exp_f32_e32 v37, v37
	v_add_f32_e32 v38, v83, v150
	v_mul_f32_e32 v38, 0xbfb8aa3b, v38
	v_add_f32_e32 v42, 1.0, v42
	v_fma_f32 v41, -v37, v37, 1.0
	v_max_f32_e32 v41, 0, v41
	v_exp_f32_e32 v38, v38
	v_sqrt_f32_e32 v41, v41
	s_nop 0
	v_rcp_f32_e32 v42, v42
	v_add_f32_e32 v38, 1.0, v38
	ds_read_u16 v40, v104 offset:272
	v_add_f32_e32 v43, v82, v147
	v_mul_f32_e32 v43, 0xbfb8aa3b, v43
	v_exp_f32_e32 v43, v43
	s_waitcnt lgkmcnt(0)
	v_lshlrev_b32_e32 v40, 16, v40
	v_add_f32_e32 v39, v83, v151
	v_mul_f32_e32 v41, v105, v41
	v_rcp_f32_e32 v105, v38
	v_mul_f32_e32 v38, v42, v86
	v_mul_f32_e32 v38, 0xbfb8aa3b, v38
	v_exp_f32_e32 v38, v38
	v_mul_f32_e32 v40, v41, v40
	ds_read_u16 v41, v104 offset:544
	v_mul_f32_e32 v39, 0xbfb8aa3b, v39
	v_fma_f32 v42, -v38, v38, 1.0
	v_max_f32_e32 v42, 0, v42
	v_add_f32_e32 v43, 1.0, v43
	v_sqrt_f32_e32 v42, v42
	s_nop 0
	v_exp_f32_e32 v39, v39
	v_rcp_f32_e32 v43, v43
	s_waitcnt lgkmcnt(0)
	v_lshlrev_b32_e32 v41, 16, v41
	v_add_f32_e32 v39, 1.0, v39
	s_nop 1
	s_nop 1
	v_mul_f32_e32 v42, v105, v42
	v_mul_f32_e32 v41, v42, v41
	ds_read_u16 v42, v104 offset:816
	v_rcp_f32_e32 v104, v39
	v_mul_f32_e32 v39, v43, v86
	v_mul_f32_e32 v39, 0xbfb8aa3b, v39
	v_exp_f32_e32 v39, v39
	s_waitcnt lgkmcnt(0)
	v_lshlrev_b32_e32 v42, 16, v42
	v_fma_f32 v43, -v39, v39, 1.0
	v_max_f32_e32 v43, 0, v43
	s_nop 0
	v_sqrt_f32_e32 v43, v43
	s_nop 0
	s_nop 0
	s_nop 0
	s_nop 1
	s_nop 1
	v_mul_f32_e32 v43, v104, v43
	v_mul_f32_e32 v42, v43, v42
	s_and_b64 vcc, exec, s[8:9]
	s_cbranch_vccnz .LBB0_190
	v_fma_f32 v43, v38, v42, v41
	v_mul_f32_e32 v104, v38, v39
	v_fma_f32 v108, v37, v43, v40
	v_mul_f32_e32 v107, v37, v104
	v_fma_f32 v109, v10, v108, v36
	v_mul_f32_e32 v105, v10, v107
	s_mov_b64 s[2:3], 0
